# v23 + P3b: half of the workgroups (bit 3 of block id) start 6.5us later so load bursts and compute of the two halves alternate
# speedup vs baseline: 1.0015x; 1.0015x over previous
; DI int get_tid() { int t = threadIdx.x; asm volatile("" : "+v"(t)); return t; }
; __global__ void __launch_bounds__(512, 2) fwd_megakernel(Params p) {
;     ...
;     { const int tl = get_tid() & 63; float gq = fabsf(p.fox_q_g[tl]), gk = fabsf(p.fox_k_g[tl]);
; #pragma unroll
;       for (int o = 1; o < 64; o <<= 1) { gq = fmaxf(gq, __shfl_xor(gq, o)); gk = fmaxf(gk, __shfl_xor(gk, o)); }
;       const float bqk = 64.0f * gq * gk * 0.125f * LOG2E * 1.02f, thr2 = 150.0f + bqk;
;       if (G == 256) { const int bh = (bx & 7) * 4 + (bx >> 6), j = (bx >> 3) & 7;
;           fox_bh_setup(bh, p, lds);
;           for (int i = 3; i >= 0; --i) fox_unit(bh, j + 8 * i, p, lds, thr2); }
.LBB0_615:
	s_or_b64 exec, exec, s[20:21]
	v_readlane_b32 s0, v253, 40
	v_readlane_b32 s1, v253, 41
	s_andn2_b64 vcc, exec, s[0:1]
	s_waitcnt lgkmcnt(0)
	v_cndmask_b32_e64 v0, 0, 1, s[0:1]
	v_cmp_ne_u32_e64 s[80:81], 1, v0
	s_barrier
	s_cbranch_vccnz .LBB0_624
	s_bitcmp1_b32 s2, 3
	s_cbranch_scc0 .Ldp_p3b
	s_sleep 127
	s_sleep 86
